# NSA selected-branch loop: V frags preloaded into free regs, PV MFMAs interleaved with sum/exp VALU
# speedup vs baseline: 1.1580x; 1.0001x over previous
; #define MFMA(a, b, c) __builtin_amdgcn_mfma_f32_32x32x16_f16(__builtin_bit_cast(h16x8, (a)), __builtin_bit_cast(h16x8, (b)), (c), 0, 0, 0)
; DI unsigned pk2(float a, float b) { f2_t v = {a, b}; bf2_t r = __builtin_convertvector(v, bf2_t); return __builtin_bit_cast(unsigned, r); }
; template <int MODE> ...
;     ...
;             float ps = 0.f;
; #pragma unroll
;             for (int i = 0; i < 16; ++i) {
;               sv[i] = __builtin_amdgcn_exp2f(sv[i] - mc);
;               ps += sv[i];
;             }
;             l[nb] += ps;
; #pragma unroll
;             for (int s2 = 0; s2 < 2; ++s2) {
;               const unsigned u0 = pk2(sv[8 * s2], sv[8 * s2 + 1]), u1 = pk2(sv[8 * s2 + 2], sv[8 * s2 + 3]);
;               const unsigned u2 = pk2(sv[8 * s2 + 4], sv[8 * s2 + 5]), u3 = pk2(sv[8 * s2 + 6], sv[8 * s2 + 7]);
;               const uint4 uu = make_uint4(u0, u1, u2, u3);
;               pk[nb][s2] = __builtin_bit_cast(bf16x8, uu);
;             }
;           }
;         }
;         if (MODE != M_CMP2) {
; #pragma unroll
;           for (int s2 = 0; s2 < 2; ++s2) {
; #pragma unroll
;             for (int db = 0; db < 2; ++db) {
;               const u16* vp = Vt + (kb * 32 + 16 * s2 + 4 * h + q4) * LDK + db * 32 + 16 * blk + 4 * p4;
;               const s16x4 lo = __builtin_amdgcn_ds_read_tr16_b64_v4i16((__attribute__((address_space(3))) s16x4*)(vp));
;               const s16x4 hi = __builtin_amdgcn_ds_read_tr16_b64_v4i16((__attribute__((address_space(3))) s16x4*)(vp + 8 * LDK));
;               const bf16x8 a = __builtin_shufflevector(lo, hi, 0, 1, 2, 3, 4, 5, 6, 7);
;               O[db][0] = MFMA(a, pk[0][s2], O[db][0]);
;               O[db][1] = MFMA(a, pk[1][s2], O[db][1]);
;             }
;           }
.LBB0_729:
	v_or_b32_e32 v244, s17, v189
	v_mad_u32_u24 v244, v244, s76, v206
	ds_read_b64_tr_b16 v[228:229], v244 offset:18432
	ds_read_b64_tr_b16 v[230:231], v244 offset:19584
	ds_read_b64_tr_b16 v[232:233], v244 offset:18496
	ds_read_b64_tr_b16 v[234:235], v244 offset:19648
	ds_read_b64_tr_b16 v[236:237], v244 offset:20736
	ds_read_b64_tr_b16 v[238:239], v244 offset:21888
	ds_read_b64_tr_b16 v[240:241], v244 offset:20800
	ds_read_b64_tr_b16 v[242:243], v244 offset:21952
	v_cvt_pk_f16_f32 v10, v208, v210
	v_cvt_pk_f16_f32 v11, v212, v213
	v_cvt_pk_f16_f32 v12, v214, v164
	v_cvt_pk_f16_f32 v13, v166, v167
	v_cvt_pk_f16_f32 v246, v165, v215
	v_cvt_pk_f16_f32 v247, v216, v217
	v_cvt_pk_f16_f32 v248, v6, v7
	v_cvt_pk_f16_f32 v249, v8, v9
	s_waitcnt lgkmcnt(6)
	v_mfma_f32_32x32x16_f16 v[64:79], v[228:231], v[10:13], v[64:79]
	v_add_f32_e32 v2, 0, v208
	v_add_f32_e32 v2, v210, v2
	v_add_f32_e32 v2, v212, v2
	v_add_f32_e32 v2, v213, v2
	v_add_f32_e32 v2, v214, v2
	v_add_f32_e32 v2, v164, v2
	v_add_f32_e32 v2, v166, v2
	v_add_f32_e32 v2, v167, v2
	s_waitcnt lgkmcnt(4)
	v_mfma_f32_32x32x16_f16 v[48:63], v[232:235], v[10:13], v[48:63]
	v_add_f32_e32 v2, v165, v2
	v_add_f32_e32 v2, v215, v2
	v_add_f32_e32 v2, v216, v2
	v_add_f32_e32 v2, v217, v2
	v_add_f32_e32 v2, v6, v2
	v_add_f32_e32 v2, v7, v2
	v_add_f32_e32 v2, v8, v2
	v_add_f32_e32 v2, v9, v2
	v_add_f32_e32 v14, v14, v2
	s_waitcnt lgkmcnt(2)
	v_mfma_f32_32x32x16_f16 v[64:79], v[236:239], v[246:249], v[64:79]
	v_sub_f32_e32 v80, v80, v205
	v_exp_f32_e32 v80, v80
	v_sub_f32_e32 v81, v81, v205
	v_exp_f32_e32 v81, v81
	v_add_f32_e32 v245, 0, v80
	v_sub_f32_e32 v82, v82, v205
	v_exp_f32_e32 v82, v82
	v_add_f32_e32 v245, v81, v245
	v_sub_f32_e32 v83, v83, v205
	s_waitcnt lgkmcnt(0)
	v_mfma_f32_32x32x16_f16 v[48:63], v[240:243], v[246:249], v[48:63]
	v_exp_f32_e32 v83, v83
	v_add_f32_e32 v245, v82, v245
	v_sub_f32_e32 v84, v84, v205
	v_exp_f32_e32 v84, v84
	v_add_f32_e32 v245, v83, v245
	v_sub_f32_e32 v85, v85, v205
	v_exp_f32_e32 v85, v85
	v_add_f32_e32 v245, v84, v245
	v_sub_f32_e32 v86, v86, v205
	v_exp_f32_e32 v86, v86
	v_add_f32_e32 v245, v85, v245
	v_sub_f32_e32 v87, v87, v205
	v_exp_f32_e32 v87, v87
	v_add_f32_e32 v245, v86, v245
	v_cvt_pk_f16_f32 v2, v80, v81
	v_cvt_pk_f16_f32 v3, v82, v83
	v_cvt_pk_f16_f32 v4, v84, v85
	v_cvt_pk_f16_f32 v5, v86, v87
	s_nop 1
	v_mfma_f32_32x32x16_f16 v[32:47], v[228:231], v[2:5], v[32:47]
	v_sub_f32_e32 v88, v88, v205
	v_exp_f32_e32 v88, v88
	v_add_f32_e32 v245, v87, v245
	v_sub_f32_e32 v89, v89, v205
	v_exp_f32_e32 v89, v89
	v_add_f32_e32 v245, v88, v245
	v_sub_f32_e32 v90, v90, v205
	v_exp_f32_e32 v90, v90
	v_add_f32_e32 v245, v89, v245
	v_mfma_f32_32x32x16_f16 v[16:31], v[232:235], v[2:5], v[16:31]
	v_sub_f32_e32 v91, v91, v205
	v_exp_f32_e32 v91, v91
	v_add_f32_e32 v245, v90, v245
	v_sub_f32_e32 v92, v92, v205
	v_exp_f32_e32 v92, v92
	v_add_f32_e32 v245, v91, v245
	v_sub_f32_e32 v93, v93, v205
	v_exp_f32_e32 v93, v93
	v_add_f32_e32 v245, v92, v245
	v_sub_f32_e32 v94, v94, v205
	v_exp_f32_e32 v94, v94
	v_add_f32_e32 v245, v93, v245
	v_sub_f32_e32 v95, v95, v205
	v_exp_f32_e32 v95, v95
	v_add_f32_e32 v245, v94, v245
	v_add_f32_e32 v245, v95, v245
	v_cvt_pk_f16_f32 v6, v88, v89
	v_cvt_pk_f16_f32 v7, v90, v91
	v_cvt_pk_f16_f32 v8, v92, v93
	v_cvt_pk_f16_f32 v9, v94, v95
	v_add_f32_e32 v180, v180, v245
	s_nop 1
	v_mfma_f32_32x32x16_f16 v[32:47], v[236:239], v[6:9], v[32:47]
	v_mfma_f32_32x32x16_f16 v[16:31], v[240:243], v[6:9], v[16:31]
	v_mov_b32_e32 v80, v14
